# nt cache policy on the gate-GEMM epilogue's read-once u loads (16 loads), otherwise the P2b-ring version
# baseline (speedup 1.0000x reference)
.LBB0_365:
	s_ashr_i32 s12, s76, 1
	v_mov_b32_e32 v129, v148
	v_mov_b32_e32 v128, v149
	s_and_b32 s52, s12, 0xffffff80
	s_cmp_lt_i32 s79, 1
	v_add_u32_e32 v155, s58, v129
	v_lshl_add_u32 v156, v128, 3, s59
	s_cbranch_scc1 .LBB0_369
	s_mov_b64 s[48:49], 0
	s_cmp_eq_u32 s79, 1
	s_mov_b64 s[50:51], 0
	s_cbranch_scc0 .LBB0_368
	v_add_u32_e32 v128, s52, v155
	v_ashrrev_i32_e32 v129, 31, v128
	v_add_u32_e32 v144, s76, v156
	v_add_u32_e32 v130, s75, v155
	s_waitcnt lgkmcnt(0)
	v_lshl_add_u64 v[128:129], v[128:129], 2, s[4:5]
	v_mov_b64_e32 v[146:147], s[14:15]
	v_ashrrev_i32_e32 v145, 31, v144
	global_load_dword v157, v[128:129], off
	v_mad_i64_i32 v[162:163], s[50:51], v130, s62, v[146:147]
	v_lshlrev_b64 v[128:129], 1, v[144:145]
	v_lshl_add_u64 v[158:159], v[162:163], 0, v[128:129]
	flat_load_dwordx4 v[158:161], v[158:159] nt
	v_ashrrev_i32_e32 v131, 31, v130
	v_add_u32_e32 v144, 0x80, v144
	v_lshlrev_b64 v[130:131], 12, v[130:131]
	v_ashrrev_i32_e32 v145, 31, v144
	v_lshl_add_u64 v[166:167], s[38:39], 0, v[130:131]
	v_lshlrev_b64 v[130:131], 1, v[144:145]
	v_lshl_add_u64 v[168:169], v[166:167], 0, v[128:129]
	v_lshl_add_u64 v[162:163], v[162:163], 0, v[130:131]
	global_load_dwordx4 v[236:239], v[162:163], off nt
	v_add_u32_e32 v176, 16, v155
	v_add_u32_e32 v178, s75, v176
	v_mad_i64_i32 v[180:181], s[50:51], v178, s62, v[146:147]
	v_lshl_add_u64 v[174:175], v[180:181], 0, v[128:129]
	global_load_dwordx4 v[244:247], v[174:175], off nt
	v_add_u32_e32 v184, 16, v155
	v_add_u32_e32 v182, s52, v184
	v_ashrrev_i32_e32 v183, 31, v182
	v_lshl_add_u64 v[182:183], v[182:183], 2, s[4:5]
	global_load_dword v248, v[182:183], off
	s_waitcnt vmcnt(3)
	v_add_u32_e32 v176, 16, v155
	v_add_u32_e32 v178, s75, v176
	v_mad_i64_i32 v[180:181], s[50:51], v178, s62, v[146:147]
	v_lshl_add_u64 v[174:175], v[180:181], 0, v[130:131]
	global_load_dwordx4 v[228:231], v[174:175], off nt
	v_add_f32_e32 v123, v123, v157
	v_add_f32_e32 v124, v124, v157
	v_add_f32_e32 v125, v125, v157
	v_add_f32_e32 v126, v126, v157
	v_add_f32_e32 v127, v127, v157
	s_waitcnt lgkmcnt(0)
	v_lshlrev_b32_e32 v173, 16, v161
	v_and_b32_e32 v161, 0xffff0000, v161
	v_add_f32_e32 v120, v120, v157
	v_add_f32_e32 v121, v121, v157
	v_add_f32_e32 v122, v122, v157
	v_lshlrev_b32_e32 v170, 16, v158
	v_and_b32_e32 v158, 0xffff0000, v158
	v_lshlrev_b32_e32 v171, 16, v159
	v_and_b32_e32 v159, 0xffff0000, v159
	v_lshlrev_b32_e32 v172, 16, v160
	v_and_b32_e32 v160, 0xffff0000, v160
	v_mul_f32_e32 v123, v123, v161
	v_mul_f32_e32 v124, v124, v170
	v_mul_f32_e32 v125, v125, v158
	v_mul_f32_e32 v126, v126, v171
	v_mul_f32_e32 v127, v127, v159
	v_mul_f32_e32 v158, v120, v172
	v_mul_f32_e32 v159, v121, v160
	v_mul_f32_e32 v160, v122, v173
	v_cvt_pk_bf16_f32 v120, v124, v125
	v_cvt_pk_bf16_f32 v121, v126, v127
	v_cvt_pk_bf16_f32 v122, v158, v159
	v_cvt_pk_bf16_f32 v123, v160, v123
	flat_store_dwordx4 v[168:169], v[120:123]
	v_add_f32_e32 v116, v116, v157
	v_add_f32_e32 v117, v117, v157
	v_add_f32_e32 v118, v118, v157
	v_add_f32_e32 v119, v119, v157
	v_add_f32_e32 v112, v112, v157
	v_add_f32_e32 v113, v113, v157
	v_add_f32_e32 v114, v114, v157
	v_add_f32_e32 v115, v115, v157
	v_add_u32_e32 v125, 16, v155
	v_add_u32_e32 v124, s75, v125
	v_lshl_add_u64 v[160:161], v[166:167], 0, v[130:131]
	v_mad_i64_i32 v[126:127], s[50:51], v124, s62, v[146:147]
	v_lshl_add_u64 v[158:159], v[126:127], 0, v[128:129]
	s_waitcnt vmcnt(4) lgkmcnt(0)
	s_nop 1
	v_mov_b32_e32 v120, v236
	v_mov_b32_e32 v121, v237
	v_mov_b32_e32 v122, v238
	v_mov_b32_e32 v123, v239
	v_add_u32_e32 v176, 32, v155
	v_add_u32_e32 v178, s75, v176
	v_mad_i64_i32 v[180:181], s[50:51], v178, s62, v[146:147]
	v_lshl_add_u64 v[174:175], v[180:181], 0, v[128:129]
	global_load_dwordx4 v[236:239], v[174:175], off nt
	v_add_u32_e32 v184, 32, v155
	v_add_u32_e32 v182, s52, v184
	v_ashrrev_i32_e32 v183, 31, v182
	v_lshl_add_u64 v[182:183], v[182:183], 2, s[4:5]
	global_load_dword v240, v[182:183], off
	v_lshlrev_b32_e32 v157, 16, v120
	v_and_b32_e32 v120, 0xffff0000, v120
	v_lshlrev_b32_e32 v163, 16, v122
	v_mul_f32_e32 v116, v116, v157
	v_lshlrev_b32_e32 v166, 16, v123
	v_and_b32_e32 v123, 0xffff0000, v123
	v_mul_f32_e32 v117, v117, v120
	v_mul_f32_e32 v120, v112, v163
	v_cvt_pk_bf16_f32 v112, v116, v117
	v_add_u32_e32 v116, s52, v125
	v_lshlrev_b32_e32 v162, 16, v121
	v_and_b32_e32 v121, 0xffff0000, v121
	v_and_b32_e32 v122, 0xffff0000, v122
	v_mul_f32_e32 v115, v115, v123
	v_ashrrev_i32_e32 v117, 31, v116
	v_mul_f32_e32 v118, v118, v162
	v_mul_f32_e32 v119, v119, v121
	v_mul_f32_e32 v121, v113, v122
	v_mul_f32_e32 v122, v114, v166
	v_cvt_pk_bf16_f32 v113, v118, v119
	v_cvt_pk_bf16_f32 v114, v120, v121
	v_cvt_pk_bf16_f32 v115, v122, v115
	flat_store_dwordx4 v[160:161], v[112:115]
	v_lshl_add_u64 v[116:117], v[116:117], 2, s[4:5]
	v_ashrrev_i32_e32 v125, 31, v124
	v_lshlrev_b64 v[116:117], 12, v[124:125]
	v_lshl_add_u64 v[116:117], s[38:39], 0, v[116:117]
	v_lshl_add_u64 v[118:119], v[126:127], 0, v[130:131]
	v_lshl_add_u64 v[120:121], v[116:117], 0, v[128:129]
	s_waitcnt vmcnt(5) lgkmcnt(0)
	s_nop 1
	v_mov_b32_e32 v112, v244
	v_mov_b32_e32 v113, v245
	v_mov_b32_e32 v114, v246
	v_mov_b32_e32 v115, v247
	v_mov_b32_e32 v122, v248
	v_add_u32_e32 v176, 32, v155
	v_add_u32_e32 v178, s75, v176
	v_mad_i64_i32 v[180:181], s[50:51], v178, s62, v[146:147]
	v_lshl_add_u64 v[174:175], v[180:181], 0, v[130:131]
	global_load_dwordx4 v[244:247], v[174:175], off nt
	v_lshlrev_b32_e32 v126, 16, v115
	v_and_b32_e32 v115, 0xffff0000, v115
	v_add_f32_e32 v107, v107, v122
	v_lshlrev_b32_e32 v123, 16, v112
	v_and_b32_e32 v112, 0xffff0000, v112
	v_lshlrev_b32_e32 v124, 16, v113
	v_and_b32_e32 v113, 0xffff0000, v113
	v_lshlrev_b32_e32 v125, 16, v114
	v_and_b32_e32 v114, 0xffff0000, v114
	v_add_f32_e32 v108, v108, v122
	v_add_f32_e32 v109, v109, v122
	v_add_f32_e32 v110, v110, v122
	v_add_f32_e32 v111, v111, v122
	v_add_f32_e32 v104, v104, v122
	v_add_f32_e32 v105, v105, v122
	v_add_f32_e32 v106, v106, v122
	v_mul_f32_e32 v107, v107, v115
	v_mul_f32_e32 v108, v108, v123
	v_mul_f32_e32 v109, v109, v112
	v_mul_f32_e32 v110, v110, v124
	v_mul_f32_e32 v111, v111, v113
	v_mul_f32_e32 v112, v104, v125
	v_mul_f32_e32 v113, v105, v114
	v_mul_f32_e32 v114, v106, v126
	v_cvt_pk_bf16_f32 v104, v108, v109
	v_cvt_pk_bf16_f32 v105, v110, v111
	v_cvt_pk_bf16_f32 v106, v112, v113
	v_cvt_pk_bf16_f32 v107, v114, v107
	flat_store_dwordx4 v[120:121], v[104:107]
	v_lshl_add_u64 v[114:115], v[116:117], 0, v[130:131]
	v_add_f32_e32 v100, v100, v122
	v_add_u32_e32 v109, 32, v155
	v_add_f32_e32 v101, v101, v122
	v_add_f32_e32 v96, v96, v122
	v_add_u32_e32 v108, s75, v109
	v_add_f32_e32 v99, v99, v122
	v_mad_i64_i32 v[110:111], s[50:51], v108, s62, v[146:147]
	v_add_f32_e32 v102, v102, v122
	v_add_f32_e32 v103, v103, v122
	v_add_f32_e32 v97, v97, v122
	v_add_f32_e32 v98, v98, v122
	v_lshl_add_u64 v[112:113], v[110:111], 0, v[128:129]
	s_waitcnt vmcnt(6) lgkmcnt(0)
	s_nop 1
	v_mov_b32_e32 v104, v228
	v_mov_b32_e32 v105, v229
	v_mov_b32_e32 v106, v230
	v_mov_b32_e32 v107, v231
	v_add_u32_e32 v176, 48, v155
	v_add_u32_e32 v178, s75, v176
	v_mad_i64_i32 v[180:181], s[50:51], v178, s62, v[146:147]
	v_lshl_add_u64 v[174:175], v[180:181], 0, v[128:129]
	global_load_dwordx4 v[228:231], v[174:175], off nt
	v_add_u32_e32 v184, 48, v155
	v_add_u32_e32 v182, s52, v184
	v_ashrrev_i32_e32 v183, 31, v182
	v_lshl_add_u64 v[182:183], v[182:183], 2, s[4:5]
	global_load_dword v232, v[182:183], off
	v_lshlrev_b32_e32 v116, 16, v104
	v_and_b32_e32 v104, 0xffff0000, v104
	v_lshlrev_b32_e32 v118, 16, v106
	v_mul_f32_e32 v100, v100, v116
	v_lshlrev_b32_e32 v119, 16, v107
	v_and_b32_e32 v107, 0xffff0000, v107
	v_mul_f32_e32 v101, v101, v104
	v_mul_f32_e32 v104, v96, v118
	v_cvt_pk_bf16_f32 v96, v100, v101
	v_add_u32_e32 v100, s52, v109
	v_lshlrev_b32_e32 v117, 16, v105
	v_and_b32_e32 v105, 0xffff0000, v105
	v_and_b32_e32 v106, 0xffff0000, v106
	v_mul_f32_e32 v99, v99, v107
	v_ashrrev_i32_e32 v101, 31, v100
	v_mul_f32_e32 v102, v102, v117
	v_mul_f32_e32 v103, v103, v105
	v_mul_f32_e32 v105, v97, v106
	v_mul_f32_e32 v106, v98, v119
	v_cvt_pk_bf16_f32 v97, v102, v103
	v_cvt_pk_bf16_f32 v98, v104, v105
	v_cvt_pk_bf16_f32 v99, v106, v99
	flat_store_dwordx4 v[114:115], v[96:99]
	v_lshl_add_u64 v[100:101], v[100:101], 2, s[4:5]
	v_ashrrev_i32_e32 v109, 31, v108
	v_lshlrev_b64 v[100:101], 12, v[108:109]
	v_lshl_add_u64 v[100:101], s[38:39], 0, v[100:101]
	v_lshl_add_u64 v[102:103], v[110:111], 0, v[130:131]
	v_lshl_add_u64 v[104:105], v[100:101], 0, v[128:129]
	s_waitcnt vmcnt(6) lgkmcnt(0)
	s_nop 1
	v_mov_b32_e32 v96, v236
	v_mov_b32_e32 v97, v237
	v_mov_b32_e32 v98, v238
	v_mov_b32_e32 v99, v239
	v_mov_b32_e32 v106, v240
	v_add_u32_e32 v176, 48, v155
	v_add_u32_e32 v178, s75, v176
	v_mad_i64_i32 v[180:181], s[50:51], v178, s62, v[146:147]
	v_lshl_add_u64 v[174:175], v[180:181], 0, v[130:131]
	global_load_dwordx4 v[236:239], v[174:175], off nt
	v_lshlrev_b32_e32 v110, 16, v99
	v_and_b32_e32 v99, 0xffff0000, v99
	v_add_f32_e32 v91, v91, v106
	v_lshlrev_b32_e32 v107, 16, v96
	v_and_b32_e32 v96, 0xffff0000, v96
	v_lshlrev_b32_e32 v108, 16, v97
	v_and_b32_e32 v97, 0xffff0000, v97
	v_lshlrev_b32_e32 v109, 16, v98
	v_and_b32_e32 v98, 0xffff0000, v98
	v_add_f32_e32 v92, v92, v106
	v_add_f32_e32 v93, v93, v106
	v_add_f32_e32 v94, v94, v106
	v_add_f32_e32 v95, v95, v106
	v_add_f32_e32 v88, v88, v106
	v_add_f32_e32 v89, v89, v106
	v_add_f32_e32 v90, v90, v106
	v_mul_f32_e32 v91, v91, v99
	v_mul_f32_e32 v92, v92, v107
	v_mul_f32_e32 v93, v93, v96
	v_mul_f32_e32 v94, v94, v108
	v_mul_f32_e32 v95, v95, v97
	v_mul_f32_e32 v96, v88, v109
	v_mul_f32_e32 v97, v89, v98
	v_mul_f32_e32 v98, v90, v110
	v_cvt_pk_bf16_f32 v88, v92, v93
	v_cvt_pk_bf16_f32 v89, v94, v95
	v_cvt_pk_bf16_f32 v90, v96, v97
	v_cvt_pk_bf16_f32 v91, v98, v91
	flat_store_dwordx4 v[104:105], v[88:91]
	v_lshl_add_u64 v[98:99], v[100:101], 0, v[130:131]
	v_add_f32_e32 v84, v84, v106
	v_add_u32_e32 v93, 48, v155
	v_add_f32_e32 v85, v85, v106
	v_add_f32_e32 v80, v80, v106
	v_add_u32_e32 v92, s75, v93
	v_add_f32_e32 v83, v83, v106
	v_mad_i64_i32 v[94:95], s[50:51], v92, s62, v[146:147]
	v_add_f32_e32 v86, v86, v106
	v_add_f32_e32 v87, v87, v106
	v_add_f32_e32 v81, v81, v106
	v_add_f32_e32 v82, v82, v106
	v_lshl_add_u64 v[96:97], v[94:95], 0, v[128:129]
	s_mov_b64 s[50:51], -1
	s_waitcnt vmcnt(6) lgkmcnt(0)
	s_nop 1
	v_mov_b32_e32 v88, v244
	v_mov_b32_e32 v89, v245
	v_mov_b32_e32 v90, v246
	v_mov_b32_e32 v91, v247
	v_lshlrev_b32_e32 v100, 16, v88
	v_and_b32_e32 v88, 0xffff0000, v88
	v_lshlrev_b32_e32 v102, 16, v90
	v_mul_f32_e32 v84, v84, v100
	v_lshlrev_b32_e32 v103, 16, v91
	v_and_b32_e32 v91, 0xffff0000, v91
	v_mul_f32_e32 v85, v85, v88
	v_mul_f32_e32 v88, v80, v102
	v_cvt_pk_bf16_f32 v80, v84, v85
	v_add_u32_e32 v84, s52, v93
	v_lshlrev_b32_e32 v101, 16, v89
	v_and_b32_e32 v89, 0xffff0000, v89
	v_and_b32_e32 v90, 0xffff0000, v90
	v_mul_f32_e32 v83, v83, v91
	v_ashrrev_i32_e32 v85, 31, v84
	v_mul_f32_e32 v86, v86, v101
	v_mul_f32_e32 v87, v87, v89
	v_mul_f32_e32 v89, v81, v90
	v_mul_f32_e32 v90, v82, v103
	v_cvt_pk_bf16_f32 v81, v86, v87
	v_cvt_pk_bf16_f32 v82, v88, v89
	v_cvt_pk_bf16_f32 v83, v90, v83
	flat_store_dwordx4 v[98:99], v[80:83]
	v_lshl_add_u64 v[84:85], v[84:85], 2, s[4:5]
	v_ashrrev_i32_e32 v93, 31, v92
	v_lshlrev_b64 v[146:147], 12, v[92:93]
	v_lshl_add_u64 v[84:85], s[38:39], 0, v[146:147]
	v_lshl_add_u64 v[84:85], v[84:85], 0, v[128:129]
	v_lshl_add_u64 v[86:87], v[94:95], 0, v[130:131]
	s_waitcnt vmcnt(4) lgkmcnt(0)
	s_nop 1
	v_mov_b32_e32 v80, v228
	v_mov_b32_e32 v81, v229
	v_mov_b32_e32 v82, v230
	v_mov_b32_e32 v83, v231
	v_mov_b32_e32 v88, v232
	v_lshlrev_b32_e32 v92, 16, v83
	v_and_b32_e32 v83, 0xffff0000, v83
	v_add_f32_e32 v75, v75, v88
	v_lshlrev_b32_e32 v89, 16, v80
	v_and_b32_e32 v80, 0xffff0000, v80
	v_lshlrev_b32_e32 v90, 16, v81
	v_and_b32_e32 v81, 0xffff0000, v81
	v_lshlrev_b32_e32 v91, 16, v82
	v_and_b32_e32 v82, 0xffff0000, v82
	v_add_f32_e32 v76, v76, v88
	v_add_f32_e32 v77, v77, v88
	v_add_f32_e32 v78, v78, v88
	v_add_f32_e32 v79, v79, v88
	v_add_f32_e32 v72, v72, v88
	v_add_f32_e32 v73, v73, v88
	v_add_f32_e32 v74, v74, v88
	v_mul_f32_e32 v75, v75, v83
	v_mul_f32_e32 v76, v76, v89
	v_mul_f32_e32 v77, v77, v80
	v_mul_f32_e32 v78, v78, v90
	v_mul_f32_e32 v79, v79, v81
	v_mul_f32_e32 v80, v72, v91
	v_mul_f32_e32 v81, v73, v82
	v_mul_f32_e32 v82, v74, v92
	v_cvt_pk_bf16_f32 v72, v76, v77
	v_cvt_pk_bf16_f32 v73, v78, v79
	v_cvt_pk_bf16_f32 v74, v80, v81
	v_cvt_pk_bf16_f32 v75, v82, v75
	flat_store_dwordx4 v[84:85], v[72:75]
	v_add_f32_e32 v68, v68, v88
	v_add_f32_e32 v69, v69, v88
	v_add_f32_e32 v70, v70, v88
	v_add_f32_e32 v71, v71, v88
	v_add_f32_e32 v64, v64, v88
	v_add_f32_e32 v65, v65, v88
	v_add_f32_e32 v66, v66, v88
	v_add_f32_e32 v67, v67, v88
	s_waitcnt vmcnt(3) lgkmcnt(0)
	s_nop 1
	v_mov_b32_e32 v72, v236
	v_mov_b32_e32 v73, v237
	v_mov_b32_e32 v74, v238
	v_mov_b32_e32 v75, v239
	v_lshlrev_b32_e32 v76, 16, v72
	v_and_b32_e32 v72, 0xffff0000, v72
	v_lshlrev_b32_e32 v77, 16, v73
	v_and_b32_e32 v73, 0xffff0000, v73
	v_lshlrev_b32_e32 v78, 16, v74
	v_and_b32_e32 v74, 0xffff0000, v74
	v_lshlrev_b32_e32 v79, 16, v75
	v_and_b32_e32 v75, 0xffff0000, v75
	v_mul_f32_e32 v68, v68, v76
	v_mul_f32_e32 v69, v69, v72
	v_mul_f32_e32 v70, v70, v77
	v_mul_f32_e32 v71, v71, v73
	v_mul_f32_e32 v64, v64, v78
	v_mul_f32_e32 v65, v65, v74
	v_mul_f32_e32 v66, v66, v79
	v_mul_f32_e32 v67, v67, v75
	v_cvt_pk_bf16_f32 v128, v68, v69
	v_cvt_pk_bf16_f32 v129, v70, v71
	v_cvt_pk_bf16_f32 v130, v64, v65
	v_cvt_pk_bf16_f32 v131, v66, v67

.LBB0_377:
	v_add_u32_e32 v64, s52, v155
	v_ashrrev_i32_e32 v65, 31, v64
	v_add_u32_e32 v74, s76, v156
	v_add_u32_e32 v66, s75, v155
	s_waitcnt lgkmcnt(0)
	v_lshl_add_u64 v[64:65], v[64:65], 2, s[4:5]
	v_mov_b64_e32 v[68:69], s[14:15]
	v_ashrrev_i32_e32 v75, 31, v74
	global_load_dword v80, v[64:65], off
	v_mad_i64_i32 v[76:77], s[48:49], v66, s62, v[68:69]
	v_lshlrev_b64 v[64:65], 1, v[74:75]
	v_lshl_add_u64 v[70:71], v[76:77], 0, v[64:65]
	flat_load_dwordx4 v[70:73], v[70:71] nt
	v_ashrrev_i32_e32 v67, 31, v66
	v_add_u32_e32 v144, 0x80, v74
	v_lshlrev_b64 v[66:67], 12, v[66:67]
	v_ashrrev_i32_e32 v145, 31, v144
	v_lshl_add_u64 v[74:75], s[38:39], 0, v[66:67]
	v_lshlrev_b64 v[66:67], 1, v[144:145]
	v_lshl_add_u64 v[78:79], v[74:75], 0, v[64:65]
	v_lshl_add_u64 v[76:77], v[76:77], 0, v[66:67]
	global_load_dwordx4 v[236:239], v[76:77], off nt
	v_add_u32_e32 v176, 16, v155
	v_add_u32_e32 v178, s75, v176
	v_mad_i64_i32 v[180:181], s[48:49], v178, s62, v[68:69]
	v_lshl_add_u64 v[174:175], v[180:181], 0, v[64:65]
	global_load_dwordx4 v[244:247], v[174:175], off nt
	v_add_u32_e32 v184, 16, v155
	v_add_u32_e32 v182, s52, v184
	v_ashrrev_i32_e32 v183, 31, v182
	v_lshl_add_u64 v[182:183], v[182:183], 2, s[4:5]
	global_load_dword v248, v[182:183], off
	s_waitcnt vmcnt(3)
	v_add_u32_e32 v176, 16, v155
	v_add_u32_e32 v178, s75, v176
	v_mad_i64_i32 v[180:181], s[48:49], v178, s62, v[68:69]
	v_lshl_add_u64 v[174:175], v[180:181], 0, v[66:67]
	global_load_dwordx4 v[228:231], v[174:175], off nt
	v_add_f32_e32 v59, v59, v80
	v_add_f32_e32 v60, v60, v80
	v_add_f32_e32 v61, v61, v80
	v_add_f32_e32 v62, v62, v80
	v_add_f32_e32 v63, v63, v80
	s_waitcnt lgkmcnt(0)
	v_lshlrev_b32_e32 v84, 16, v73
	v_and_b32_e32 v73, 0xffff0000, v73
	v_add_f32_e32 v56, v56, v80
	v_add_f32_e32 v57, v57, v80
	v_add_f32_e32 v58, v58, v80
	v_lshlrev_b32_e32 v81, 16, v70
	v_and_b32_e32 v70, 0xffff0000, v70
	v_lshlrev_b32_e32 v82, 16, v71
	v_and_b32_e32 v71, 0xffff0000, v71
	v_lshlrev_b32_e32 v83, 16, v72
	v_and_b32_e32 v72, 0xffff0000, v72
	v_mul_f32_e32 v59, v59, v73
	v_mul_f32_e32 v60, v60, v81
	v_mul_f32_e32 v61, v61, v70
	v_mul_f32_e32 v62, v62, v82
	v_mul_f32_e32 v63, v63, v71
	v_mul_f32_e32 v70, v56, v83
	v_mul_f32_e32 v71, v57, v72
	v_mul_f32_e32 v72, v58, v84
	v_cvt_pk_bf16_f32 v56, v60, v61
	v_cvt_pk_bf16_f32 v57, v62, v63
	v_cvt_pk_bf16_f32 v58, v70, v71
	v_cvt_pk_bf16_f32 v59, v72, v59
	flat_store_dwordx4 v[78:79], v[56:59]
	v_lshl_add_u64 v[72:73], v[74:75], 0, v[66:67]
	v_add_f32_e32 v52, v52, v80
	v_add_u32_e32 v61, 16, v155
	v_add_f32_e32 v53, v53, v80
	v_add_f32_e32 v48, v48, v80
	v_add_u32_e32 v60, s75, v61
	v_add_f32_e32 v51, v51, v80
	v_mad_i64_i32 v[62:63], s[48:49], v60, s62, v[68:69]
	v_add_f32_e32 v54, v54, v80
	v_add_f32_e32 v55, v55, v80
	v_add_f32_e32 v49, v49, v80
	v_add_f32_e32 v50, v50, v80
	v_lshl_add_u64 v[70:71], v[62:63], 0, v[64:65]
	s_waitcnt vmcnt(4) lgkmcnt(0)
	s_nop 1
	v_mov_b32_e32 v56, v236
	v_mov_b32_e32 v57, v237
	v_mov_b32_e32 v58, v238
	v_mov_b32_e32 v59, v239
	v_add_u32_e32 v176, 32, v155
	v_add_u32_e32 v178, s75, v176
	v_mad_i64_i32 v[180:181], s[48:49], v178, s62, v[68:69]
	v_lshl_add_u64 v[174:175], v[180:181], 0, v[64:65]
	global_load_dwordx4 v[236:239], v[174:175], off nt
	v_add_u32_e32 v184, 32, v155
	v_add_u32_e32 v182, s52, v184
	v_ashrrev_i32_e32 v183, 31, v182
	v_lshl_add_u64 v[182:183], v[182:183], 2, s[4:5]
	global_load_dword v240, v[182:183], off
	v_lshlrev_b32_e32 v74, 16, v56
	v_and_b32_e32 v56, 0xffff0000, v56
	v_lshlrev_b32_e32 v76, 16, v58
	v_mul_f32_e32 v52, v52, v74
	v_lshlrev_b32_e32 v77, 16, v59
	v_and_b32_e32 v59, 0xffff0000, v59
	v_mul_f32_e32 v53, v53, v56
	v_mul_f32_e32 v56, v48, v76
	v_cvt_pk_bf16_f32 v48, v52, v53
	v_add_u32_e32 v52, s52, v61
	v_lshlrev_b32_e32 v75, 16, v57
	v_and_b32_e32 v57, 0xffff0000, v57
	v_and_b32_e32 v58, 0xffff0000, v58
	v_mul_f32_e32 v51, v51, v59
	v_ashrrev_i32_e32 v53, 31, v52
	v_mul_f32_e32 v54, v54, v75
	v_mul_f32_e32 v55, v55, v57
	v_mul_f32_e32 v57, v49, v58
	v_mul_f32_e32 v58, v50, v77
	v_cvt_pk_bf16_f32 v49, v54, v55
	v_cvt_pk_bf16_f32 v50, v56, v57
	v_cvt_pk_bf16_f32 v51, v58, v51
	flat_store_dwordx4 v[72:73], v[48:51]
	v_lshl_add_u64 v[52:53], v[52:53], 2, s[4:5]
	v_ashrrev_i32_e32 v61, 31, v60
	v_lshlrev_b64 v[52:53], 12, v[60:61]
	v_lshl_add_u64 v[52:53], s[38:39], 0, v[52:53]
	v_lshl_add_u64 v[54:55], v[62:63], 0, v[66:67]
	v_lshl_add_u64 v[56:57], v[52:53], 0, v[64:65]
	s_waitcnt vmcnt(5) lgkmcnt(0)
	s_nop 1
	v_mov_b32_e32 v48, v244
	v_mov_b32_e32 v49, v245
	v_mov_b32_e32 v50, v246
	v_mov_b32_e32 v51, v247
	v_mov_b32_e32 v58, v248
	v_add_u32_e32 v176, 32, v155
	v_add_u32_e32 v178, s75, v176
	v_mad_i64_i32 v[180:181], s[48:49], v178, s62, v[68:69]
	v_lshl_add_u64 v[174:175], v[180:181], 0, v[66:67]
	global_load_dwordx4 v[244:247], v[174:175], off nt
	v_lshlrev_b32_e32 v62, 16, v51
	v_and_b32_e32 v51, 0xffff0000, v51
	v_add_f32_e32 v43, v43, v58
	v_lshlrev_b32_e32 v59, 16, v48
	v_and_b32_e32 v48, 0xffff0000, v48
	v_lshlrev_b32_e32 v60, 16, v49
	v_and_b32_e32 v49, 0xffff0000, v49
	v_lshlrev_b32_e32 v61, 16, v50
	v_and_b32_e32 v50, 0xffff0000, v50
	v_add_f32_e32 v44, v44, v58
	v_add_f32_e32 v45, v45, v58
	v_add_f32_e32 v46, v46, v58
	v_add_f32_e32 v47, v47, v58
	v_add_f32_e32 v40, v40, v58
	v_add_f32_e32 v41, v41, v58
	v_add_f32_e32 v42, v42, v58
	v_mul_f32_e32 v43, v43, v51
	v_mul_f32_e32 v44, v44, v59
	v_mul_f32_e32 v45, v45, v48
	v_mul_f32_e32 v46, v46, v60
	v_mul_f32_e32 v47, v47, v49
	v_mul_f32_e32 v48, v40, v61
	v_mul_f32_e32 v49, v41, v50
	v_mul_f32_e32 v50, v42, v62
	v_cvt_pk_bf16_f32 v40, v44, v45
	v_cvt_pk_bf16_f32 v41, v46, v47
	v_cvt_pk_bf16_f32 v42, v48, v49
	v_cvt_pk_bf16_f32 v43, v50, v43
	flat_store_dwordx4 v[56:57], v[40:43]
	v_lshl_add_u64 v[50:51], v[52:53], 0, v[66:67]
	v_add_f32_e32 v36, v36, v58
	v_add_u32_e32 v45, 32, v155
	v_add_f32_e32 v37, v37, v58
	v_add_f32_e32 v32, v32, v58
	v_add_u32_e32 v44, s75, v45
	v_add_f32_e32 v35, v35, v58
	v_mad_i64_i32 v[46:47], s[48:49], v44, s62, v[68:69]
	v_add_f32_e32 v38, v38, v58
	v_add_f32_e32 v39, v39, v58
	v_add_f32_e32 v33, v33, v58
	v_add_f32_e32 v34, v34, v58
	v_lshl_add_u64 v[48:49], v[46:47], 0, v[64:65]
	s_waitcnt vmcnt(6) lgkmcnt(0)
	s_nop 1
	v_mov_b32_e32 v40, v228
	v_mov_b32_e32 v41, v229
	v_mov_b32_e32 v42, v230
	v_mov_b32_e32 v43, v231
	v_add_u32_e32 v176, 48, v155
	v_add_u32_e32 v178, s75, v176
	v_mad_i64_i32 v[180:181], s[48:49], v178, s62, v[68:69]
	v_lshl_add_u64 v[174:175], v[180:181], 0, v[64:65]
	global_load_dwordx4 v[228:231], v[174:175], off nt
	v_add_u32_e32 v184, 48, v155
	v_add_u32_e32 v182, s52, v184
	v_ashrrev_i32_e32 v183, 31, v182
	v_lshl_add_u64 v[182:183], v[182:183], 2, s[4:5]
	global_load_dword v232, v[182:183], off
	v_lshlrev_b32_e32 v52, 16, v40
	v_and_b32_e32 v40, 0xffff0000, v40
	v_lshlrev_b32_e32 v54, 16, v42
	v_mul_f32_e32 v36, v36, v52
	v_lshlrev_b32_e32 v55, 16, v43
	v_and_b32_e32 v43, 0xffff0000, v43
	v_mul_f32_e32 v37, v37, v40
	v_mul_f32_e32 v40, v32, v54
	v_cvt_pk_bf16_f32 v32, v36, v37
	v_add_u32_e32 v36, s52, v45
	v_lshlrev_b32_e32 v53, 16, v41
	v_and_b32_e32 v41, 0xffff0000, v41
	v_and_b32_e32 v42, 0xffff0000, v42
	v_mul_f32_e32 v35, v35, v43
	v_ashrrev_i32_e32 v37, 31, v36
	v_mul_f32_e32 v38, v38, v53
	v_mul_f32_e32 v39, v39, v41
	v_mul_f32_e32 v41, v33, v42
	v_mul_f32_e32 v42, v34, v55
	v_cvt_pk_bf16_f32 v33, v38, v39
	v_cvt_pk_bf16_f32 v34, v40, v41
	v_cvt_pk_bf16_f32 v35, v42, v35
	flat_store_dwordx4 v[50:51], v[32:35]
	v_lshl_add_u64 v[36:37], v[36:37], 2, s[4:5]
	v_ashrrev_i32_e32 v45, 31, v44
	v_lshlrev_b64 v[36:37], 12, v[44:45]
	v_lshl_add_u64 v[36:37], s[38:39], 0, v[36:37]
	v_lshl_add_u64 v[38:39], v[46:47], 0, v[66:67]
	v_lshl_add_u64 v[40:41], v[36:37], 0, v[64:65]
	s_waitcnt vmcnt(6) lgkmcnt(0)
	s_nop 1
	v_mov_b32_e32 v32, v236
	v_mov_b32_e32 v33, v237
	v_mov_b32_e32 v34, v238
	v_mov_b32_e32 v35, v239
	v_mov_b32_e32 v42, v240
	v_add_u32_e32 v176, 48, v155
	v_add_u32_e32 v178, s75, v176
	v_mad_i64_i32 v[180:181], s[48:49], v178, s62, v[68:69]
	v_lshl_add_u64 v[174:175], v[180:181], 0, v[66:67]
	global_load_dwordx4 v[236:239], v[174:175], off nt
	v_lshlrev_b32_e32 v46, 16, v35
	v_and_b32_e32 v35, 0xffff0000, v35
	v_add_f32_e32 v27, v27, v42
	v_lshlrev_b32_e32 v43, 16, v32
	v_and_b32_e32 v32, 0xffff0000, v32
	v_lshlrev_b32_e32 v44, 16, v33
	v_and_b32_e32 v33, 0xffff0000, v33
	v_lshlrev_b32_e32 v45, 16, v34
	v_and_b32_e32 v34, 0xffff0000, v34
	v_add_f32_e32 v28, v28, v42
	v_add_f32_e32 v29, v29, v42
	v_add_f32_e32 v30, v30, v42
	v_add_f32_e32 v31, v31, v42
	v_add_f32_e32 v24, v24, v42
	v_add_f32_e32 v25, v25, v42
	v_add_f32_e32 v26, v26, v42
	v_mul_f32_e32 v27, v27, v35
	v_mul_f32_e32 v28, v28, v43
	v_mul_f32_e32 v29, v29, v32
	v_mul_f32_e32 v30, v30, v44
	v_mul_f32_e32 v31, v31, v33
	v_mul_f32_e32 v32, v24, v45
	v_mul_f32_e32 v33, v25, v34
	v_mul_f32_e32 v34, v26, v46
	v_cvt_pk_bf16_f32 v24, v28, v29
	v_cvt_pk_bf16_f32 v25, v30, v31
	v_cvt_pk_bf16_f32 v26, v32, v33
	v_cvt_pk_bf16_f32 v27, v34, v27
	flat_store_dwordx4 v[40:41], v[24:27]
	v_lshl_add_u64 v[34:35], v[36:37], 0, v[66:67]
	v_add_f32_e32 v20, v20, v42
	v_add_u32_e32 v29, 48, v155
	v_add_f32_e32 v21, v21, v42
	v_add_f32_e32 v16, v16, v42
	v_add_u32_e32 v28, s75, v29
	v_add_f32_e32 v19, v19, v42
	v_mad_i64_i32 v[30:31], s[48:49], v28, s62, v[68:69]
	v_add_f32_e32 v22, v22, v42
	v_add_f32_e32 v23, v23, v42
	v_add_f32_e32 v17, v17, v42
	v_add_f32_e32 v18, v18, v42
	v_lshl_add_u64 v[32:33], v[30:31], 0, v[64:65]
	s_waitcnt vmcnt(6) lgkmcnt(0)
	s_nop 1
	v_mov_b32_e32 v24, v244
	v_mov_b32_e32 v25, v245
	v_mov_b32_e32 v26, v246
	v_mov_b32_e32 v27, v247
	v_lshlrev_b32_e32 v36, 16, v24
	v_and_b32_e32 v24, 0xffff0000, v24
	v_lshlrev_b32_e32 v38, 16, v26
	v_mul_f32_e32 v20, v20, v36
	v_lshlrev_b32_e32 v39, 16, v27
	v_and_b32_e32 v27, 0xffff0000, v27
	v_mul_f32_e32 v21, v21, v24
	v_mul_f32_e32 v24, v16, v38
	v_cvt_pk_bf16_f32 v16, v20, v21
	v_add_u32_e32 v20, s52, v29
	v_lshlrev_b32_e32 v37, 16, v25
	v_and_b32_e32 v25, 0xffff0000, v25
	v_and_b32_e32 v26, 0xffff0000, v26
	v_mul_f32_e32 v19, v19, v27
	v_ashrrev_i32_e32 v21, 31, v20
	v_mul_f32_e32 v22, v22, v37
	v_mul_f32_e32 v23, v23, v25
	v_mul_f32_e32 v25, v17, v26
	v_mul_f32_e32 v26, v18, v39
	v_cvt_pk_bf16_f32 v17, v22, v23
	v_cvt_pk_bf16_f32 v18, v24, v25
	v_cvt_pk_bf16_f32 v19, v26, v19
	flat_store_dwordx4 v[34:35], v[16:19]
	v_lshl_add_u64 v[20:21], v[20:21], 2, s[4:5]
	v_ashrrev_i32_e32 v29, 31, v28
	v_lshlrev_b64 v[146:147], 12, v[28:29]
	v_lshl_add_u64 v[20:21], s[38:39], 0, v[146:147]
	v_lshl_add_u64 v[20:21], v[20:21], 0, v[64:65]
	v_lshl_add_u64 v[22:23], v[30:31], 0, v[66:67]
	s_waitcnt vmcnt(4) lgkmcnt(0)
	s_nop 1
	v_mov_b32_e32 v16, v228
	v_mov_b32_e32 v17, v229
	v_mov_b32_e32 v18, v230
	v_mov_b32_e32 v19, v231
	v_mov_b32_e32 v24, v232
	v_lshlrev_b32_e32 v28, 16, v19
	v_and_b32_e32 v19, 0xffff0000, v19
	v_add_f32_e32 v11, v11, v24
	v_lshlrev_b32_e32 v25, 16, v16
	v_and_b32_e32 v16, 0xffff0000, v16
	v_lshlrev_b32_e32 v26, 16, v17
	v_and_b32_e32 v17, 0xffff0000, v17
	v_lshlrev_b32_e32 v27, 16, v18
	v_and_b32_e32 v18, 0xffff0000, v18
	v_add_f32_e32 v12, v12, v24
	v_add_f32_e32 v13, v13, v24
	v_add_f32_e32 v14, v14, v24
	v_add_f32_e32 v15, v15, v24
	v_add_f32_e32 v8, v8, v24
	v_add_f32_e32 v9, v9, v24
	v_add_f32_e32 v10, v10, v24
	v_mul_f32_e32 v11, v11, v19
	v_mul_f32_e32 v12, v12, v25
	v_mul_f32_e32 v13, v13, v16
	v_mul_f32_e32 v14, v14, v26
	v_mul_f32_e32 v15, v15, v17
	v_mul_f32_e32 v16, v8, v27
	v_mul_f32_e32 v17, v9, v18
	v_mul_f32_e32 v18, v10, v28
	v_cvt_pk_bf16_f32 v8, v12, v13
	v_cvt_pk_bf16_f32 v9, v14, v15
	v_cvt_pk_bf16_f32 v10, v16, v17
	v_cvt_pk_bf16_f32 v11, v18, v11
	flat_store_dwordx4 v[20:21], v[8:11]
	v_add_f32_e32 v4, v4, v24
	v_add_f32_e32 v5, v5, v24
	v_add_f32_e32 v6, v6, v24
	v_add_f32_e32 v7, v7, v24
	v_add_f32_e32 v0, v0, v24
	v_add_f32_e32 v1, v1, v24
	v_add_f32_e32 v2, v2, v24
	v_add_f32_e32 v3, v3, v24
	s_waitcnt vmcnt(3) lgkmcnt(0)
	s_nop 1
	v_mov_b32_e32 v8, v236
	v_mov_b32_e32 v9, v237
	v_mov_b32_e32 v10, v238
	v_mov_b32_e32 v11, v239
	v_lshlrev_b32_e32 v12, 16, v8
	v_and_b32_e32 v8, 0xffff0000, v8
	v_lshlrev_b32_e32 v13, 16, v9
	v_and_b32_e32 v9, 0xffff0000, v9
	v_lshlrev_b32_e32 v14, 16, v10
	v_and_b32_e32 v10, 0xffff0000, v10
	v_lshlrev_b32_e32 v15, 16, v11
	v_and_b32_e32 v11, 0xffff0000, v11
	v_mul_f32_e32 v4, v4, v12
	v_mul_f32_e32 v5, v5, v8
	v_mul_f32_e32 v6, v6, v13
	v_mul_f32_e32 v7, v7, v9
	v_mul_f32_e32 v0, v0, v14
	v_mul_f32_e32 v1, v1, v10
	v_mul_f32_e32 v2, v2, v15
	v_mul_f32_e32 v3, v3, v11
	v_cvt_pk_bf16_f32 v128, v4, v5
	v_cvt_pk_bf16_f32 v129, v6, v7
	v_cvt_pk_bf16_f32 v130, v0, v1
	v_cvt_pk_bf16_f32 v131, v2, v3
	s_cbranch_execnz .LBB0_372
	s_branch .LBB0_373
